# SWA prompt unit: the 8 masked K/V staging loads issued together (one round trip instead of six)
# baseline (speedup 1.0000x reference)
.LBB0_112:
	s_andn2_b64 vcc, exec, s[4:5]
	s_cbranch_vccnz .LBB0_81
	v_readlane_b32 s4, v255, 4
	v_readlane_b32 s5, v255, 5
	s_andn2_b64 vcc, exec, s[4:5]
	s_cbranch_vccnz .LBB0_81
	v_readlane_b32 s8, v254, 25
	v_readlane_b32 s10, v254, 27
	v_readlane_b32 s11, v254, 28
	s_ashr_i32 s6, s0, 1
	s_mov_b64 s[4:5], s[10:11]
	s_add_u32 s10, s4, 0xc700000
	s_addc_u32 s11, s5, 0
	s_and_b32 s14, s6, 3
	s_bfe_u32 s12, s6, 0x40002
	s_ashr_i32 s6, s0, 7
	v_readlane_b32 s9, v254, 26
	s_ashr_i32 s7, s6, 31
	s_lshl_b64 s[8:9], s[6:7], 11
	s_lshl_b32 s7, s12, 7
	s_or_b32 s0, s8, s7
	s_mul_i32 s8, s9, 0xc00
	s_mul_hi_u32 s9, s0, 0xc00
	s_add_i32 s9, s9, s8
	s_mulk_i32 s0, 0xc00
	s_add_u32 s0, s10, s0
	s_addc_u32 s8, s11, s9
	s_lshl_b32 s9, s14, 7
	s_add_u32 s0, s0, s9
	s_addc_u32 s9, s8, 0
	s_add_u32 s8, s0, 0xfffa0800
	s_addc_u32 s9, s9, -1
	s_cmp_eq_u32 s12, 0
	s_cselect_b32 s0, 0x80, 0
	v_mov_b64_e32 v[194:195], 0
	v_mov_b64_e32 v[196:197], 0
	v_mov_b64_e32 v[198:199], 0
	v_mov_b64_e32 v[200:201], 0
	v_mov_b64_e32 v[202:203], 0
	v_mov_b64_e32 v[204:205], 0
	v_mov_b64_e32 v[206:207], 0
	v_mov_b64_e32 v[208:209], 0
	v_mov_b64_e32 v[210:211], 0
	v_mov_b64_e32 v[212:213], 0
	v_mov_b64_e32 v[214:215], 0
	v_mov_b64_e32 v[216:217], 0
	v_mov_b64_e32 v[218:219], 0
	v_mov_b64_e32 v[220:221], 0
	v_mov_b64_e32 v[222:223], 0
	v_mov_b64_e32 v[224:225], 0
	v_cmp_le_i32_e32 vcc, s0, v70
	v_lshl_add_u64 v[226:227], s[8:9], 0, v[36:37]
	v_lshl_add_u64 v[226:227], v[38:39], 1, v[226:227]
	s_and_saveexec_b64 s[12:13], vcc
	global_load_dwordx4 v[194:197], v[226:227], off
	s_or_b64 exec, exec, s[12:13]
	v_cmp_le_i32_e32 vcc, s0, v71
	v_lshl_add_u64 v[226:227], s[8:9], 0, v[40:41]
	v_lshl_add_u64 v[226:227], v[42:43], 1, v[226:227]
	s_and_saveexec_b64 s[12:13], vcc
	global_load_dwordx4 v[198:201], v[226:227], off
	s_or_b64 exec, exec, s[12:13]
	v_cmp_le_i32_e32 vcc, s0, v72
	v_lshl_add_u64 v[226:227], s[8:9], 0, v[44:45]
	v_lshl_add_u64 v[226:227], v[46:47], 1, v[226:227]
	s_and_saveexec_b64 s[12:13], vcc
	global_load_dwordx4 v[202:205], v[226:227], off
	s_or_b64 exec, exec, s[12:13]
	v_cmp_le_i32_e32 vcc, s0, v73
	v_lshl_add_u64 v[226:227], s[8:9], 0, v[48:49]
	v_lshl_add_u64 v[226:227], v[50:51], 1, v[226:227]
	s_and_saveexec_b64 s[12:13], vcc
	global_load_dwordx4 v[206:209], v[226:227], off
	s_or_b64 exec, exec, s[12:13]
	v_cmp_le_i32_e32 vcc, s0, v74
	v_lshl_add_u64 v[226:227], s[8:9], 0, v[52:53]
	v_lshl_add_u64 v[226:227], v[54:55], 1, v[226:227]
	s_and_saveexec_b64 s[12:13], vcc
	global_load_dwordx4 v[210:213], v[226:227], off offset:512
	s_or_b64 exec, exec, s[12:13]
	v_cmp_le_i32_e32 vcc, s0, v75
	v_lshl_add_u64 v[226:227], s[8:9], 0, v[56:57]
	v_lshl_add_u64 v[226:227], v[54:55], 1, v[226:227]
	s_and_saveexec_b64 s[12:13], vcc
	global_load_dwordx4 v[214:217], v[226:227], off offset:512
	s_or_b64 exec, exec, s[12:13]
	v_cmp_le_i32_e32 vcc, s0, v76
	v_lshl_add_u64 v[226:227], s[8:9], 0, v[58:59]
	v_lshl_add_u64 v[226:227], v[60:61], 1, v[226:227]
	s_and_saveexec_b64 s[12:13], vcc
	global_load_dwordx4 v[218:221], v[226:227], off offset:512
	s_or_b64 exec, exec, s[12:13]
	v_cmp_le_i32_e32 vcc, s0, v77
	v_lshl_add_u64 v[226:227], s[8:9], 0, v[62:63]
	v_lshl_add_u64 v[226:227], v[60:61], 1, v[226:227]
	s_and_saveexec_b64 s[12:13], vcc
	global_load_dwordx4 v[222:225], v[226:227], off offset:512
	s_or_b64 exec, exec, s[12:13]
	s_waitcnt vmcnt(0)
	ds_write_b128 v114, v[194:197]
	ds_write_b128 v115, v[198:201]
	ds_write_b128 v116, v[202:205]
	ds_write_b128 v117, v[206:209]
	v_mov_b64_e32 v[2:3], v[210:211]
	v_mov_b64_e32 v[4:5], v[212:213]
	v_mov_b64_e32 v[6:7], v[214:215]
	v_mov_b64_e32 v[8:9], v[216:217]
	v_and_b32_e32 v1, 0xffff, v2
	v_lshrrev_b32_e32 v2, 16, v2
	v_lshl_or_b32 v1, v6, 16, v1
	v_and_or_b32 v2, v6, s59, v2
	v_add_u32_e32 v6, 0x9000, v118
	ds_write2_b32 v6, v1, v2 offset1:132
	v_and_b32_e32 v1, 0xffff, v3
	v_lshrrev_b32_e32 v2, 16, v3
	v_lshl_or_b32 v1, v7, 16, v1
	v_and_or_b32 v2, v7, s59, v2
	v_add_u32_e32 v3, 0x9400, v118
	ds_write2_b32 v3, v1, v2 offset0:8 offset1:140
	v_and_b32_e32 v1, 0xffff, v4
	v_lshrrev_b32_e32 v2, 16, v4
	v_lshl_or_b32 v1, v8, 16, v1
	v_and_or_b32 v2, v8, s59, v2
	v_add_u32_e32 v3, 0x9800, v118
	ds_write2_b32 v3, v1, v2 offset0:16 offset1:148
	v_and_b32_e32 v1, 0xffff, v5
	v_lshrrev_b32_e32 v2, 16, v5
	v_lshl_or_b32 v1, v9, 16, v1
	v_and_or_b32 v2, v9, s59, v2
	v_add_u32_e32 v3, 0x9c00, v118
	ds_write2_b32 v3, v1, v2 offset0:24 offset1:156
	v_mov_b64_e32 v[0:1], v[218:219]
	v_mov_b64_e32 v[2:3], v[220:221]
	v_mov_b64_e32 v[4:5], v[222:223]
	v_mov_b64_e32 v[6:7], v[224:225]
	v_and_b32_e32 v8, 0xffff, v0
	v_lshrrev_b32_e32 v0, 16, v0
	v_lshl_or_b32 v8, v4, 16, v8
	v_and_or_b32 v0, v4, s59, v0
	v_add_u32_e32 v4, 0x9000, v119
	ds_write2_b32 v4, v8, v0 offset1:132
	v_and_b32_e32 v0, 0xffff, v1
	v_lshrrev_b32_e32 v1, 16, v1
	v_lshl_or_b32 v0, v5, 16, v0
	v_and_or_b32 v1, v5, s59, v1
	v_add_u32_e32 v4, 0x9400, v119
	ds_write2_b32 v4, v0, v1 offset0:8 offset1:140
	v_and_b32_e32 v0, 0xffff, v2
	v_lshrrev_b32_e32 v1, 16, v2
	v_lshl_or_b32 v0, v6, 16, v0
	v_and_or_b32 v1, v6, s59, v1
	v_add_u32_e32 v2, 0x9800, v119
	v_readlane_b32 s8, v255, 6
	ds_write2_b32 v2, v0, v1 offset0:16 offset1:148
	v_and_b32_e32 v0, 0xffff, v3
	v_lshrrev_b32_e32 v1, 16, v3
	v_readlane_b32 s9, v255, 7
	v_readlane_b32 s16, v254, 12
	v_lshl_or_b32 v0, v7, 16, v0
	v_and_or_b32 v1, v7, s59, v1
	v_add_u32_e32 v2, 0x9c00, v119
	s_andn2_b64 vcc, exec, s[8:9]
	s_movk_i32 s9, 0xc00
	v_readlane_b32 s18, v254, 14
	v_readlane_b32 s19, v254, 15
	ds_write2_b32 v2, v0, v1 offset0:24 offset1:156
	s_waitcnt lgkmcnt(0)
	s_barrier
	v_readlane_b32 s17, v254, 13
	v_readlane_b32 s20, v254, 16
	v_readlane_b32 s21, v254, 17
	v_readlane_b32 s22, v254, 18
	v_readlane_b32 s23, v254, 19
	s_cbranch_vccnz .LBB0_81
	s_add_u32 s4, s4, 0x17100000
	s_addc_u32 s5, s5, 0
	s_lshl_b32 s6, s6, 11
	s_or_b32 s6, s7, s6
	v_writelane_b32 v255, s6, 10
	s_lshl_b32 s6, s14, 2
	v_writelane_b32 v255, s6, 12
	v_cmp_le_u32_e64 s[6:7], s0, v80
	v_and_b32_e32 v1, 64, v188
	v_xor_b32_e32 v0, 16, v188
	v_writelane_b32 v255, s6, 14
	v_add_u32_e32 v1, 64, v1
	v_cmp_lt_i32_e32 vcc, v0, v1
	v_writelane_b32 v255, s7, 15
	v_cmp_le_u32_e64 s[6:7], s0, v81
	v_cndmask_b32_e32 v0, v188, v0, vcc
	v_lshlrev_b32_e32 v132, 2, v0
	v_writelane_b32 v255, s6, 16
	v_xor_b32_e32 v0, 32, v188
	v_cmp_lt_i32_e32 vcc, v0, v1
	v_writelane_b32 v255, s7, 17
	v_cmp_le_u32_e64 s[6:7], s0, v82
	v_cndmask_b32_e32 v0, v188, v0, vcc
	v_lshlrev_b32_e32 v133, 2, v0
	v_writelane_b32 v255, s6, 18
	v_cmp_le_u32_e64 s[52:53], s0, v90
	v_cmp_le_u32_e64 s[54:55], s0, v91
	v_writelane_b32 v255, s7, 19
	v_cmp_le_u32_e64 s[6:7], s0, v83
	v_cmp_le_u32_e64 s[14:15], s0, v92
	v_cmp_le_u32_e64 s[16:17], s0, v93
	v_writelane_b32 v255, s6, 20
	v_cmp_le_u32_e64 s[20:21], s0, v94
	v_cmp_le_u32_e64 s[22:23], s0, v95
	v_writelane_b32 v255, s7, 21
	v_cmp_le_u32_e64 s[6:7], s0, v84
	v_cmp_le_u32_e64 s[64:65], s0, v96
	v_cmp_le_u32_e64 s[66:67], s0, v97
	v_writelane_b32 v255, s6, 22
	v_cmp_le_u32_e64 s[68:69], s0, v98
	v_cmp_le_u32_e64 s[24:25], s0, v99
	v_writelane_b32 v255, s7, 23
	v_cmp_le_u32_e64 s[6:7], s0, v85
	v_cmp_le_u32_e64 s[72:73], s0, v100
	v_cmp_le_u32_e64 s[74:75], s0, v101
	v_writelane_b32 v255, s6, 24
	v_cmp_le_u32_e64 s[76:77], s0, v102
	v_cmp_le_u32_e64 s[78:79], s0, v103
	v_writelane_b32 v255, s7, 25
	v_cmp_le_u32_e64 s[6:7], s0, v86
	v_cmp_le_u32_e64 s[80:81], s0, v104
	v_cmp_le_u32_e64 s[82:83], s0, v105
	v_writelane_b32 v255, s6, 26
	v_cmp_le_u32_e64 s[84:85], s0, v106
	v_cmp_le_u32_e64 s[86:87], s0, v107
	v_writelane_b32 v255, s7, 27
	v_cmp_le_u32_e64 s[6:7], s0, v87
	v_cmp_le_u32_e64 s[88:89], s0, v108
	v_cmp_le_u32_e64 s[90:91], s0, v109
	v_writelane_b32 v255, s6, 28
	v_cmp_le_u32_e64 s[92:93], s0, v110
	v_cmp_le_u32_e64 s[94:95], s0, v111
	v_writelane_b32 v255, s7, 29
	v_cmp_le_u32_e64 s[6:7], s0, v88
	v_readlane_b32 s71, v254, 58
	s_nop 0
	v_writelane_b32 v255, s6, 30
	s_nop 1
	v_writelane_b32 v255, s7, 31
	v_cmp_le_u32_e64 s[6:7], s0, v89
	s_nop 1
	v_writelane_b32 v255, s6, 32
	s_nop 1
	v_writelane_b32 v255, s7, 33
	s_nop 0
	v_readlane_b32 s0, v255, 8
